# attention A: K/V tile loads use SGPR base + 32-bit lane offset (no per-step VALU address math); includes GEMM saddr loads and GEMM setprio removal
# speedup vs baseline: 1.0154x; 1.0072x over previous
; #define FLAS __attribute__((address_space(3)))
; __device__ __forceinline__ void attn_unit_a(FLAS unsigned char* lds, const Unit u) {
;     ...
;     const FLAS float* L = (const FLAS float*)(lds + LA_LUT);
;     const f32x16 z16 = {0.f,0.f,0.f,0.f,0.f,0.f,0.f,0.f,0.f,0.f,0.f,0.f,0.f,0.f,0.f,0.f};
;     f32x16 o[NDB];
; #pragma unroll
;     for (int i = 0; i < NDB; ++i) o[i] = z16;
;     float mrun = 0.f, lsum = 0.f, fpend = 1.f; bool first = true, pend = false;
;     ...
;     f32x16 pa0, pa1, pb0, pb1; float cbC = 0.f;
;     { bool zi; FA_BIAS(0, pa0, pa1, cbC, zi); if (zi) { pa0 = z16; pa1 = z16; }
;       const FLAS unsigned char* kb = lds + LA_K;
; #pragma unroll
;       for (int d0 = 0; d0 < 4; ++d0) { const int ko = (2 * d0 + hi) * 1024 + ((r32 ^ (2 * d0 + hi)) * 16); const bf16x8 a0 = *(const FLAS bf16x8*)(kb + ko), a1 = *(const FLAS bf16x8*)(kb + ko + 512);
;           pa0 = __builtin_amdgcn_mfma_f32_32x32x16_bf16(a0, qr[d0], pa0, 0, 0, 0); pa1 = __builtin_amdgcn_mfma_f32_32x32x16_bf16(a1, qr[d0], pa1, 0, 0, 0); } }
;     u32x4 pwa[4] = {{0u,0u,0u,0u},{0u,0u,0u,0u},{0u,0u,0u,0u},{0u,0u,0u,0u}}, pwb[4] = {{0u,0u,0u,0u},{0u,0u,0u,0u},{0u,0u,0u,0u},{0u,0u,0u,0u}};
;     auto step = [&](const int i, f32x16& pC0, f32x16& pC1, f32x16& pN0, f32x16& pN1, u32x4 (&PWC)[4], u32x4 (&PWN)[4]) __attribute__((always_inline)) {
;         if (pend) {
; #pragma unroll
;             for (int d = 0; d < NDB; ++d) o[d] = o[d] * fpend;
;             pend = false; }
;         if (i + 2 < NT) { kreg = *(const u32x4*)(ksrc + (size_t)(u.t_lo + i + 2) * 64 * u.ldk);
; #pragma unroll
;             for (int j = 0; j < 2; ++j) vreg[j] = *(const u32x4*)(vsrc + (size_t)j * 64 * MTOK + (u.t_lo + i + 2) * 64); }
;         const int vsp = (i == 0) ? 0 : ((i - 1) & 3);
;         const FLAS unsigned char* vb_ = lds + LA_V + vsp * VBUF + r32 * VPITCH + hi * 16;
;         const FLAS unsigned char* kb = lds + LA_K + ((i + 1) & 1) * KBUF;
;     ...
;         u32x4 vr[3];
; #pragma unroll
;         for (int m = 0; m < 3; ++m) vr[m] = FA_VFRAG(m);
;         const float off = cbC - mrun;
.Lprio_skip:
	s_waitcnt lgkmcnt(0)
	v_readlane_b32 s100, v254, 47
	v_mov_b32_e32 v92, s13
	s_nop 3
	v_mov_b32_e32 v93, s100
	ds_read_b32 v92, v92
	ds_read_b32 v93, v93
	v_sub_f32_e32 v94, v204, v211
	v_add_f32_e32 v96, v128, v94
	v_add_f32_e32 v112, v144, v94
	v_add_f32_e32 v97, v129, v94
	v_add_f32_e32 v113, v145, v94
	v_add_f32_e32 v98, v130, v94
	v_add_f32_e32 v114, v146, v94
	v_add_f32_e32 v99, v131, v94
	v_add_f32_e32 v115, v147, v94
	v_add_f32_e32 v100, v132, v94
	v_add_f32_e32 v116, v148, v94
	v_add_f32_e32 v101, v133, v94
	v_add_f32_e32 v117, v149, v94
	v_add_f32_e32 v102, v134, v94
	v_add_f32_e32 v118, v150, v94
	v_add_f32_e32 v103, v135, v94
	v_add_f32_e32 v119, v151, v94
	v_add_f32_e32 v104, v136, v94
	v_add_f32_e32 v120, v152, v94
	v_add_f32_e32 v105, v137, v94
	v_add_f32_e32 v121, v153, v94
	v_add_f32_e32 v106, v138, v94
	v_add_f32_e32 v122, v154, v94
	v_add_f32_e32 v107, v139, v94
	v_add_f32_e32 v123, v155, v94
	v_add_f32_e32 v108, v140, v94
	v_add_f32_e32 v124, v156, v94
	v_add_f32_e32 v109, v141, v94
	v_add_f32_e32 v125, v157, v94
	v_add_f32_e32 v110, v142, v94
	v_add_f32_e32 v126, v158, v94
	v_add_f32_e32 v111, v143, v94
	v_add_f32_e32 v127, v159, v94
	v_mov_b32_e32 v144, 0x7fc00000
	v_mov_b32_e32 v145, 0x7fc00000
	v_mov_b32_e32 v146, 0x7fc00000
	v_mov_b32_e32 v147, 0x7fc00000
	v_mov_b32_e32 v148, 0x7fc00000
	v_mov_b32_e32 v149, 0x7fc00000
	v_mov_b32_e32 v150, 0x7fc00000
	v_mov_b32_e32 v151, 0x7fc00000
	v_mov_b32_e32 v152, 0x7fc00000
	v_mov_b32_e32 v153, 0x7fc00000
	v_mov_b32_e32 v154, 0x7fc00000
	v_mov_b32_e32 v155, 0x7fc00000
	v_mov_b32_e32 v156, 0x7fc00000
	v_mov_b32_e32 v157, 0x7fc00000
	v_mov_b32_e32 v158, 0x7fc00000
	v_mov_b32_e32 v159, 0x7fc00000
	v_mov_b32_e32 v204, 0
	v_mov_b32_e32 v205, 0
	v_mov_b32_e32 v206, 0
	v_mov_b32_e32 v207, 0
	s_waitcnt lgkmcnt(0)
	v_readfirstlane_b32 s101, v92
	v_readfirstlane_b32 s100, v93
	v_mov_b32_e32 v72, 0
	v_mov_b32_e32 v73, 0
	v_mov_b32_e32 v74, 0
	v_mov_b32_e32 v75, 0
	v_mov_b32_e32 v76, 0
	v_mov_b32_e32 v77, 0
	v_mov_b32_e32 v78, 0
	v_mov_b32_e32 v79, 0
	v_mov_b32_e32 v80, 0
	v_mov_b32_e32 v81, 0
	v_mov_b32_e32 v82, 0
	v_mov_b32_e32 v83, 0
	v_mov_b32_e32 v84, 0
	v_mov_b32_e32 v85, 0
	v_mov_b32_e32 v86, 0
	v_mov_b32_e32 v87, 0
	v_mov_b32_e32 v88, 0
	v_mov_b32_e32 v89, 0
	v_mov_b32_e32 v90, 0
	v_mov_b32_e32 v91, 0
	v_mov_b32_e32 v92, 0
	v_mov_b32_e32 v93, 0
	v_mov_b32_e32 v94, 0
	v_mov_b32_e32 v95, 0
	v_writelane_b32 v255, s50, 30
	v_writelane_b32 v255, s51, 31
	v_writelane_b32 v255, s52, 32
	v_writelane_b32 v255, s53, 33
	v_readfirstlane_b32 s50, v230
	v_readfirstlane_b32 s51, v231
	v_readfirstlane_b32 s52, v228
	v_readfirstlane_b32 s53, v229
	s_nop 3
	v_subrev_u32_e32 v230, s50, v230
	v_subrev_u32_e32 v228, s52, v228
	v_add_u32_e32 v230, v230, v208
	v_add_u32_e32 v228, v228, v208
	v_add_u32_e32 v231, 0x30000, v230
	v_add_u32_e32 v229, 0x400000, v228
	s_add_u32 s50, s50, 0xd660000
	s_addc_u32 s51, s51, 0
	s_add_u32 s52, s52, 0x13600000
	s_addc_u32 s53, s53, 0
	s_mov_b32 s99, 0x7fc00000
	s_add_i32 s12, s19, -1
	s_and_b32 s18, s12, 3
	s_mulk_i32 s18, 0x4800
	s_cmp_lg_u32 s49, 0
	s_cselect_b32 s12, s18, 0
	v_add_u32_e32 v200, s12, v251
	ds_read_b128 v[128:131], v200 offset:16384
	ds_read_b128 v[132:135], v200 offset:20992
	ds_read_b128 v[136:139], v200 offset:25600
	s_cbranch_execnz .LBB0_435
	s_branch .LBB0_434

; #define FLAS __attribute__((address_space(3)))
; #define FA_SB() __builtin_amdgcn_sched_barrier(0)
; __device__ __forceinline__ float fadd_s(float a, float b) { float r; asm("v_add_f32_e32 %0, %1, %2" : "=v"(r) : "v"(a), "v"(b)); return r; }
; #define FA_PVM(G) do { o[(G) & 3] = __builtin_amdgcn_mfma_f32_32x32x16_bf16(__builtin_bit_cast(bf16x8, vr[(G) % 3]), __builtin_bit_cast(bf16x8, PWC[(G) >> 2]), o[(G) & 3], 0, 0, 0); if ((G) + 3 < 16) vr[(G) % 3] = FA_VFRAG((G) + 3); } while (0)
; __device__ __forceinline__ void attn_unit_a(FLAS unsigned char* lds, const Unit u) {
;     ...
;         if (i + 2 < NT) { kreg = *(const u32x4*)(ksrc + (size_t)(u.t_lo + i + 2) * 64 * u.ldk);
; #pragma unroll
;             for (int j = 0; j < 2; ++j) vreg[j] = *(const u32x4*)(vsrc + (size_t)j * 64 * MTOK + (u.t_lo + i + 2) * 64); }
;         const int vsp = (i == 0) ? 0 : ((i - 1) & 3);
;         const FLAS unsigned char* vb_ = lds + LA_V + vsp * VBUF + r32 * VPITCH + hi * 16;
;         const FLAS unsigned char* kb = lds + LA_K + ((i + 1) & 1) * KBUF;
;     ...
;         u32x4 vr[3];
; #pragma unroll
;         for (int m = 0; m < 3; ++m) vr[m] = FA_VFRAG(m);
;         const float off = cbC - mrun;
;         FA_SB();
;         float ra, rb, rm;
;         FA_PVM(0); pC0[0] = fadd_s(pC0[0], off); pC1[0] = fadd_s(pC1[0], off); pC0[1] = fadd_s(pC0[1], off); pC1[1] = fadd_s(pC1[1], off); pC0[2] = fadd_s(pC0[2], off); pC1[2] = fadd_s(pC1[2], off); FA_SB();
.LBB0_435:
	s_cmpk_lt_u32 s19, 0x7e
	s_cselect_b64 s[0:1], -1, 0
	s_cmpk_gt_u32 s19, 0x7d
	s_cselect_b64 s[4:5], -1, 0
	s_xor_b64 s[20:21], s[24:25], -1
	s_waitcnt lgkmcnt(1)
	v_mfma_f32_32x32x16_bf16 v[48:63], v[128:131], v[204:207], v[48:63]
	ds_read_b128 v[128:131], v200 offset:30208
	s_and_b64 vcc, exec, s[4:5]
	s_cbranch_vccnz .LBB0_437
	global_load_dwordx4 v[176:179], v230, s[50:51]
	global_load_dwordx4 v[180:183], v228, s[52:53] offset:256
	global_load_dwordx4 v[184:187], v229, s[52:53] offset:256

; #define FLAS __attribute__((address_space(3)))
; #define FA_SB() __builtin_amdgcn_sched_barrier(0)
; __device__ __forceinline__ float fadd_s(float a, float b) { float r; asm("v_add_f32_e32 %0, %1, %2" : "=v"(r) : "v"(a), "v"(b)); return r; }
; #define FA_PVM(G) do { o[(G) & 3] = __builtin_amdgcn_mfma_f32_32x32x16_bf16(__builtin_bit_cast(bf16x8, vr[(G) % 3]), __builtin_bit_cast(bf16x8, PWC[(G) >> 2]), o[(G) & 3], 0, 0, 0); if ((G) + 3 < 16) vr[(G) % 3] = FA_VFRAG((G) + 3); } while (0)
; __device__ __forceinline__ void attn_unit_a(FLAS unsigned char* lds, const Unit u) {
;     ...
;         if (i + 2 < NT) { kreg = *(const u32x4*)(ksrc + (size_t)(u.t_lo + i + 2) * 64 * u.ldk);
; #pragma unroll
;             for (int j = 0; j < 2; ++j) vreg[j] = *(const u32x4*)(vsrc + (size_t)j * 64 * MTOK + (u.t_lo + i + 2) * 64); }
;         const int vsp = (i == 0) ? 0 : ((i - 1) & 3);
;         const FLAS unsigned char* vb_ = lds + LA_V + vsp * VBUF + r32 * VPITCH + hi * 16;
;         const FLAS unsigned char* kb = lds + LA_K + ((i + 1) & 1) * KBUF;
;     ...
;         u32x4 vr[3];
; #pragma unroll
;         for (int m = 0; m < 3; ++m) vr[m] = FA_VFRAG(m);
;         const float off = cbC - mrun;
;         FA_SB();
;         float ra, rb, rm;
;         FA_PVM(0); pC0[0] = fadd_s(pC0[0], off); pC1[0] = fadd_s(pC1[0], off); pC0[1] = fadd_s(pC0[1], off); pC1[1] = fadd_s(pC1[1], off); pC0[2] = fadd_s(pC0[2], off); pC1[2] = fadd_s(pC1[2], off); FA_SB();
.LBB0_458:
	s_cmpk_lt_u32 s19, 0x7d
	s_cselect_b64 s[20:21], -1, 0
	s_waitcnt lgkmcnt(1)
	v_mfma_f32_32x32x16_bf16 v[48:63], v[128:131], v[140:143], v[48:63]
	ds_read_b128 v[128:131], v201 offset:30208
	s_cmpk_gt_u32 s19, 0x7c
	s_cbranch_scc1 .LBB0_460
	global_load_dwordx4 v[176:179], v231, s[50:51]
	global_load_dwordx4 v[180:183], v228, s[52:53] offset:384
	global_load_dwordx4 v[184:187], v229, s[52:53] offset:384

; #define FLAS __attribute__((address_space(3)))
; __device__ __forceinline__ void attn_unit_a(FLAS unsigned char* lds, const Unit u) {
;     ...
;         lsum += ps; cbC = cbN;
;         if (i + 2 < NT) { *(FLAS u32x4*)(lds + LA_K + (i & 1) * KBUF + kdst) = kreg;
; #pragma unroll
;             for (int j = 0; j < 2; ++j) { *(FLAS u32x2*)(lds + LA_V + ((i + 2) & 3) * VBUF + vdst + j * 64 * VPITCH) = (u32x2){vreg[j].x, vreg[j].y}; *(FLAS u32x2*)(lds + LA_V + ((i + 2) & 3) * VBUF + vdst + j * 64 * VPITCH + 16) = (u32x2){vreg[j].z, vreg[j].w}; } }
;         __syncthreads();
;     };
;     for (int i = 0; i < NT; i += 2) { step(i, pa0, pa1, pb0, pb1, pwa, pwb); if (i + 1 < NT) step(i + 1, pb0, pb1, pa0, pa1, pwb, pwa); }
;     if (pend) {
; #pragma unroll
;         for (int d = 0; d < NDB; ++d) o[d] = o[d] * fpend; }
.LBB0_476:
	s_add_u32 s52, s52, 0x100
	s_addc_u32 s53, s53, 0
	v_cvt_pk_bf16_f32 v206, v68, v69
	v_cvt_pk_bf16_f32 v207, v70, v71
	s_addk_i32 s48, 0x80
	s_addk_i32 s49, 0x200
	s_add_u32 s50, s50, 0x60000
	s_addc_u32 s51, s51, 0
	s_mov_b64 s[24:25], 0
	s_and_b64 vcc, exec, s[4:5]
	v_cvt_pk_bf16_f32 v204, v64, v65
	v_cvt_pk_bf16_f32 v205, v66, v67
	s_waitcnt lgkmcnt(0)
	s_barrier
	s_cbranch_vccnz .Lexit_a
	s_mov_b32 s19, s34
	s_and_b64 vcc, exec, s[0:1]
	s_cbranch_vccnz .LBB0_434
	s_branch .LBB0_435
.Lexit_a:
	v_readlane_b32 s50, v255, 30
	v_readlane_b32 s51, v255, 31
	v_readlane_b32 s52, v255, 32
	v_readlane_b32 s53, v255, 33
	s_setprio 0
	s_andn2_b64 vcc, exec, s[0:1]
	s_cbranch_vccnz .LBB0_479
	v_pk_mul_f32 v[62:63], v[62:63], v[226:227] op_sel_hi:[1,0]
	v_pk_mul_f32 v[60:61], v[60:61], v[226:227] op_sel_hi:[1,0]
	v_pk_mul_f32 v[58:59], v[58:59], v[226:227] op_sel_hi:[1,0]
	v_pk_mul_f32 v[56:57], v[56:57], v[226:227] op_sel_hi:[1,0]
	v_pk_mul_f32 v[54:55], v[54:55], v[226:227] op_sel_hi:[1,0]
	v_pk_mul_f32 v[52:53], v[52:53], v[226:227] op_sel_hi:[1,0]
	v_pk_mul_f32 v[50:51], v[50:51], v[226:227] op_sel_hi:[1,0]
	v_pk_mul_f32 v[48:49], v[48:49], v[226:227] op_sel_hi:[1,0]
	v_pk_mul_f32 v[46:47], v[46:47], v[226:227] op_sel_hi:[1,0]
	v_pk_mul_f32 v[44:45], v[44:45], v[226:227] op_sel_hi:[1,0]
	v_pk_mul_f32 v[42:43], v[42:43], v[226:227] op_sel_hi:[1,0]
	v_pk_mul_f32 v[40:41], v[40:41], v[226:227] op_sel_hi:[1,0]
	v_pk_mul_f32 v[38:39], v[38:39], v[226:227] op_sel_hi:[1,0]
	v_pk_mul_f32 v[36:37], v[36:37], v[226:227] op_sel_hi:[1,0]
	v_pk_mul_f32 v[34:35], v[34:35], v[226:227] op_sel_hi:[1,0]
	v_pk_mul_f32 v[32:33], v[32:33], v[226:227] op_sel_hi:[1,0]
	v_pk_mul_f32 v[30:31], v[30:31], v[226:227] op_sel_hi:[1,0]
	v_pk_mul_f32 v[28:29], v[28:29], v[226:227] op_sel_hi:[1,0]
	v_pk_mul_f32 v[26:27], v[26:27], v[226:227] op_sel_hi:[1,0]
	v_pk_mul_f32 v[24:25], v[24:25], v[226:227] op_sel_hi:[1,0]
	v_pk_mul_f32 v[22:23], v[22:23], v[226:227] op_sel_hi:[1,0]
	v_pk_mul_f32 v[20:21], v[20:21], v[226:227] op_sel_hi:[1,0]
	v_pk_mul_f32 v[18:19], v[18:19], v[226:227] op_sel_hi:[1,0]
	v_pk_mul_f32 v[16:17], v[16:17], v[226:227] op_sel_hi:[1,0]
	v_pk_mul_f32 v[14:15], v[14:15], v[226:227] op_sel_hi:[1,0]
	v_pk_mul_f32 v[12:13], v[12:13], v[226:227] op_sel_hi:[1,0]
	v_pk_mul_f32 v[10:11], v[10:11], v[226:227] op_sel_hi:[1,0]
	v_pk_mul_f32 v[8:9], v[8:9], v[226:227] op_sel_hi:[1,0]
	v_pk_mul_f32 v[6:7], v[6:7], v[226:227] op_sel_hi:[1,0]
	v_pk_mul_f32 v[4:5], v[4:5], v[226:227] op_sel_hi:[1,0]
	v_pk_mul_f32 v[2:3], v[2:3], v[226:227] op_sel_hi:[1,0]
	v_pk_mul_f32 v[0:1], v[0:1], v[226:227] op_sel_hi:[1,0]
